# mn1 and mn2 row loops: next row requested one row ahead (second register set), counted waits recounted
# baseline (speedup 1.0000x reference)
; __device__ __forceinline__ float bf_lo(unsigned u) { return __uint_as_float(u << 16); }
; __device__ __forceinline__ float bf_hi(unsigned u) { return __uint_as_float(u & 0xffff0000u); }
; __device__ __forceinline__ int vblk() { return (int)blockIdx.x * 2 + half_id(); }
; __device__ __forceinline__ int vgrid() { return (int)gridDim.x * 2; }
; __device__ void phase_modnorm(const Params& p, const float* __restrict__ src, const bf16_t* __restrict__ srcb, const float* __restrict__ g, int shift_idx, int scale_idx, bf16_t* __restrict__ dst) {
;     const int tid_ = TIDX; const int lane = tid_ & 63, wave = tid_ >> 6;
;     const float* mod = (const float*)(p.ws + OFF_MOD);
;     for (int tok = vblk() * 4 + wave; tok < NTOK; tok += vgrid() * 4) {
;         const int b = tok >> 11;
;         const float* xr = src + (size_t)tok * DM;
;         f32x4 v[4];
;         float ss = 0.f;
; #pragma unroll
;         for (int c = 0; c < 4; c++) {
;             if (srcb) {
;                 const u32x2 w = *(const u32x2*)(srcb + (size_t)tok * DM + c * 256 + lane * 4);
;                 v[c] = (f32x4){bf_lo(w.x), bf_hi(w.x), bf_lo(w.y), bf_hi(w.y)};
;             } else v[c] = *(const f32x4*)(xr + c * 256 + lane * 4);
;             ss += v[c][0] * v[c][0] + v[c][1] * v[c][1] + v[c][2] * v[c][2] + v[c][3] * v[c][3];
;         }
;         ss = wave_sum(ss);
;         const float rstd = rsqrtf(ss * (1.f / 1024.f) + 1e-6f);
.LBB0_234:
	s_or_b64 exec, exec, s[4:5]
	v_readfirstlane_b32 s0, v158
	v_readlane_b32 s1, v222, 0
	s_lshr_b32 s0, s0, 6
	s_mov_b64 s[6:7], s[80:81]
	v_mov_b32_e32 v18, v158
	s_lshl_b32 s28, s1, 3
	s_and_b32 s0, s0, 0x3fffffc
	s_waitcnt lgkmcnt(0)
	s_barrier
	s_add_i32 s0, s0, s28
	v_lshrrev_b32_e32 v0, 6, v18
	v_and_or_b32 v16, v0, 3, s0
	s_movk_i32 s0, 0x4000
	v_cmp_gt_i32_e32 vcc, s0, v16
	v_mbcnt_lo_u32_b32 v30, -1, 0
	s_and_saveexec_b64 s[4:5], vcc
	s_cbranch_execz .LBB0_237
	s_load_dwordx2 s[0:1], s[6:7], 0x28
	s_load_dwordx2 s[10:11], s[6:7], 0xd8
	v_lshlrev_b32_e32 v0, 2, v18
	v_and_b32_e32 v24, 0xfc, v0
	v_lshlrev_b32_e32 v17, 2, v24
	s_waitcnt lgkmcnt(0)
	global_load_dwordx4 v[0:3], v17, s[0:1]
	global_load_dwordx4 v[4:7], v17, s[0:1] offset:1024
	global_load_dwordx4 v[8:11], v17, s[0:1] offset:2048
	global_load_dwordx4 v[12:15], v17, s[0:1] offset:3072
	v_mbcnt_hi_u32_b32 v17, -1, v30
	v_and_b32_e32 v20, 64, v17
	v_add_u32_e32 v20, 64, v20
	v_xor_b32_e32 v21, 32, v17
	v_cmp_lt_i32_e32 vcc, v21, v20
	s_load_dwordx2 s[0:1], s[6:7], 0x0
	s_add_u32 s6, s10, 0x4000
	v_cndmask_b32_e32 v21, v17, v21, vcc
	v_lshlrev_b32_e32 v31, 2, v21
	v_xor_b32_e32 v21, 16, v17
	v_cmp_lt_i32_e32 vcc, v21, v20
	v_and_b32_e32 v18, 63, v18
	s_addc_u32 s7, s11, 0
	v_cndmask_b32_e32 v21, v17, v21, vcc
	v_lshlrev_b32_e32 v32, 2, v21
	v_xor_b32_e32 v21, 8, v17
	v_cmp_lt_i32_e32 vcc, v21, v20
	s_lshl_b32 s8, s76, 3
	v_mov_b32_e32 v19, 0
	v_cndmask_b32_e32 v21, v17, v21, vcc
	v_lshlrev_b32_e32 v33, 2, v21
	v_xor_b32_e32 v21, 4, v17
	v_cmp_lt_i32_e32 vcc, v21, v20
	v_or_b32_e32 v26, 0x100, v24
	v_or_b32_e32 v28, 0x200, v24
	v_cndmask_b32_e32 v21, v17, v21, vcc
	v_lshlrev_b32_e32 v34, 2, v21
	v_xor_b32_e32 v21, 2, v17
	v_cmp_lt_i32_e32 vcc, v21, v20
	v_or_b32_e32 v38, 0x300, v24
	s_mov_b64 s[2:3], 0x1c00000
	v_cndmask_b32_e32 v21, v17, v21, vcc
	v_lshlrev_b32_e32 v35, 2, v21
	v_xor_b32_e32 v21, 1, v17
	v_cmp_lt_i32_e32 vcc, v21, v20
	s_ashr_i32 s9, s8, 31
	s_lshl_b64 s[14:15], s[8:9], 12
	v_cndmask_b32_e32 v17, v17, v21, vcc
	v_lshlrev_b32_e32 v36, 2, v17
	v_ashrrev_i32_e32 v17, 31, v16
	v_lshlrev_b64 v[20:21], 11, v[16:17]
	v_lshlrev_b64 v[22:23], 12, v[16:17]
	v_lshl_or_b32 v20, v18, 3, v20
	v_lshl_or_b32 v22, v18, 4, v22
	v_lshl_add_u64 v[20:21], s[10:11], 0, v[20:21]
	s_waitcnt lgkmcnt(0)
	v_lshl_add_u64 v[22:23], s[0:1], 0, v[22:23]
	s_mov_b64 s[0:1], 0xc00
	v_lshl_add_u64 v[20:21], v[20:21], 0, s[2:3]
	s_lshl_b64 s[10:11], s[8:9], 11
	v_lshl_add_u64 v[22:23], v[22:23], 0, s[0:1]
	s_mov_b64 s[16:17], 0
	v_mov_b32_e32 v17, 0x358637bd
	s_mov_b32 s0, 0x800000
	s_mov_b64 s[18:19], 0x1000
	v_lshlrev_b32_e32 v18, 2, v24
	v_lshlrev_b32_e32 v24, 2, v26
	v_mov_b32_e32 v25, v19
	v_lshlrev_b32_e32 v26, 2, v28
	v_mov_b32_e32 v27, v19
	v_lshlrev_b32_e32 v28, 2, v38
	v_mov_b32_e32 v29, v19
	s_movk_i32 s1, 0x3fff
	global_load_dwordx4 v[102:105], v[22:23], off offset:-3072
	global_load_dwordx4 v[106:109], v[22:23], off offset:-2048
	global_load_dwordx4 v[110:113], v[22:23], off offset:-1024
	global_load_dwordx4 v[114:117], v[22:23], off
	s_waitcnt vmcnt(0)
	s_branch .Lmn1_body
.LBB0_236:
	s_waitcnt vmcnt(4)
; __device__ __forceinline__ float bf_lo(unsigned u) { return __uint_as_float(u << 16); }
; __device__ __forceinline__ float bf_hi(unsigned u) { return __uint_as_float(u & 0xffff0000u); }
; __device__ __forceinline__ int vblk() { return (int)blockIdx.x * 2 + half_id(); }
; __device__ __forceinline__ int vgrid() { return (int)gridDim.x * 2; }
; __device__ void phase_modnorm(const Params& p, const float* __restrict__ src, const bf16_t* __restrict__ srcb, const float* __restrict__ g, int shift_idx, int scale_idx, bf16_t* __restrict__ dst) {
;     ...
;     for (int tok = vblk() * 4 + wave; tok < NTOK; tok += vgrid() * 4) {
;         const int b = tok >> 11;
;         const float* xr = src + (size_t)tok * DM;
;         f32x4 v[4];
;         float ss = 0.f;
; #pragma unroll
;         for (int c = 0; c < 4; c++) {
;             if (srcb) {
;                 const u32x2 w = *(const u32x2*)(srcb + (size_t)tok * DM + c * 256 + lane * 4);
;                 v[c] = (f32x4){bf_lo(w.x), bf_hi(w.x), bf_lo(w.y), bf_hi(w.y)};
;             } else v[c] = *(const f32x4*)(xr + c * 256 + lane * 4);
;             ss += v[c][0] * v[c][0] + v[c][1] * v[c][1] + v[c][2] * v[c][2] + v[c][3] * v[c][3];
;         }
;         ss = wave_sum(ss);
;         const float rstd = rsqrtf(ss * (1.f / 1024.f) + 1e-6f);
; #pragma unroll
;         for (int c = 0; c < 4; c++) {
;             const int d = c * 256 + lane * 4;
;             const f32x4 gg = *(const f32x4*)(g + d);
;             const f32x4 sc = *(const f32x4*)(mod + b * 6144 + scale_idx * 1024 + d);
;             const f32x4 sh = *(const f32x4*)(mod + b * 6144 + shift_idx * 1024 + d);
;             float o[4];
; #pragma unroll
;             for (int j = 0; j < 4; j++) o[j] = (v[c][j] * rstd) * gg[j] * (1.f + sc[j]) + sh[j];
;             *(u32x2*)(dst + (size_t)tok * DM + d) = (u32x2){pack2(o[0], o[1]), pack2(o[2], o[3])};
;         }
.Lmn1_body:
	v_mov_b32_e32 v38, v102
	v_mov_b32_e32 v39, v103
	v_mov_b32_e32 v40, v104
	v_mov_b32_e32 v41, v105
	v_mov_b32_e32 v42, v106
	v_mov_b32_e32 v43, v107
	v_mov_b32_e32 v44, v108
	v_mov_b32_e32 v45, v109
	v_mov_b32_e32 v46, v110
	v_mov_b32_e32 v47, v111
	v_mov_b32_e32 v48, v112
	v_mov_b32_e32 v49, v113
	v_mov_b32_e32 v50, v114
	v_mov_b32_e32 v51, v115
	v_mov_b32_e32 v52, v116
	v_mov_b32_e32 v53, v117
	v_ashrrev_i32_e32 v37, 11, v16
	v_mul_i32_i24_e32 v54, 0x1800, v37
	v_ashrrev_i32_e32 v55, 31, v54
	v_lshl_add_u64 v[54:55], v[54:55], 2, s[6:7]
	v_lshl_add_u64 v[62:63], v[54:55], 0, s[18:19]
	v_lshl_add_u64 v[86:87], v[54:55], 0, v[18:19]
	v_lshl_add_u64 v[88:89], v[62:63], 0, v[18:19]
	v_lshl_add_u64 v[90:91], v[62:63], 0, v[24:25]
	v_lshl_add_u64 v[92:93], v[62:63], 0, v[26:27]
	global_load_dwordx4 v[54:57], v[86:87], off offset:1024
	global_load_dwordx4 v[58:61], v[86:87], off offset:2048
	v_lshl_add_u64 v[94:95], v[62:63], 0, v[28:29]
	global_load_dwordx4 v[62:65], v[88:89], off
	global_load_dwordx4 v[66:69], v[90:91], off
	global_load_dwordx4 v[70:73], v[92:93], off
	global_load_dwordx4 v[74:77], v[94:95], off
	global_load_dwordx4 v[78:81], v[86:87], off
	global_load_dwordx4 v[82:85], v[86:87], off offset:3072
	v_add_u32_e32 v16, s8, v16
	v_cmp_lt_i32_e32 vcc, s1, v16
	s_or_b64 s[16:17], vcc, s[16:17]
	v_mov_b32_e32 v118, v22
	v_mov_b32_e32 v119, v23
	v_lshl_add_u64 v[22:23], v[22:23], 0, s[14:15]
	v_cndmask_b32_e32 v118, v22, v118, vcc
	v_cndmask_b32_e32 v119, v23, v119, vcc
	global_load_dwordx4 v[102:105], v[118:119], off offset:-3072
	global_load_dwordx4 v[106:109], v[118:119], off offset:-2048
	global_load_dwordx4 v[110:113], v[118:119], off offset:-1024
	global_load_dwordx4 v[114:117], v[118:119], off
	v_mov_b32_e32 v88, v39
	v_mov_b32_e32 v89, v43
	v_mov_b32_e32 v86, v38
	v_mov_b32_e32 v87, v42
	v_mov_b32_e32 v96, v47
	v_mov_b32_e32 v97, v51
	v_pk_mul_f32 v[88:89], v[88:89], v[88:89]
	v_mov_b32_e32 v90, v40
	v_mov_b32_e32 v91, v44
	v_mov_b32_e32 v94, v46
	v_mov_b32_e32 v95, v50
	v_pk_mul_f32 v[96:97], v[96:97], v[96:97]
	v_pk_fma_f32 v[86:87], v[86:87], v[86:87], v[88:89]
	v_mov_b32_e32 v92, v41
	v_mov_b32_e32 v93, v45
	v_mov_b32_e32 v98, v48
	v_mov_b32_e32 v99, v52
	v_pk_fma_f32 v[88:89], v[94:95], v[94:95], v[96:97]
	v_pk_fma_f32 v[86:87], v[90:91], v[90:91], v[86:87]
	v_mov_b32_e32 v100, v49
	v_mov_b32_e32 v101, v53
	v_pk_fma_f32 v[88:89], v[98:99], v[98:99], v[88:89]
	v_pk_fma_f32 v[86:87], v[92:93], v[92:93], v[86:87]
	v_pk_fma_f32 v[88:89], v[100:101], v[100:101], v[88:89]
	v_add_f32_e32 v37, v86, v87
	v_add_f32_e32 v37, v37, v88
	v_add_f32_e32 v37, v37, v89
	s_nop 1
	v_add_f32_dpp v37, v37, v37 row_ror:8 row_mask:0xf bank_mask:0xf
	s_nop 1
	v_add_f32_dpp v37, v37, v37 row_ror:4 row_mask:0xf bank_mask:0xf
	s_nop 1
	v_add_f32_dpp v37, v37, v37 row_ror:2 row_mask:0xf bank_mask:0xf
	s_nop 1
	v_add_f32_dpp v37, v37, v37 row_ror:1 row_mask:0xf bank_mask:0xf
	v_mov_b32_e32 v86, v37
	s_nop 1
	v_permlane16_swap_b32_e32 v37, v86
	v_add_f32_e32 v37, v37, v86
	v_mov_b32_e32 v86, v37
	s_nop 1
	v_permlane32_swap_b32_e32 v37, v86
	v_add_f32_e32 v37, v37, v86
	s_waitcnt vmcnt(9)
	v_pk_add_f32 v[62:63], v[62:63], 1.0 op_sel_hi:[1,0]
	v_pk_add_f32 v[64:65], v[64:65], 1.0 op_sel_hi:[1,0]
	s_waitcnt vmcnt(8)
	v_pk_add_f32 v[66:67], v[66:67], 1.0 op_sel_hi:[1,0]
	v_pk_add_f32 v[68:69], v[68:69], 1.0 op_sel_hi:[1,0]
	s_waitcnt vmcnt(7)
	v_pk_add_f32 v[70:71], v[70:71], 1.0 op_sel_hi:[1,0]
	v_pk_add_f32 v[72:73], v[72:73], 1.0 op_sel_hi:[1,0]
	s_waitcnt vmcnt(6)
	v_pk_add_f32 v[74:75], v[74:75], 1.0 op_sel_hi:[1,0]
	v_pk_add_f32 v[76:77], v[76:77], 1.0 op_sel_hi:[1,0]
	v_fmamk_f32 v37, v37, 0x3a800000, v17
	v_mul_f32_e32 v86, 0x4b800000, v37
	v_cmp_gt_f32_e32 vcc, s0, v37
	s_nop 1
	v_cndmask_b32_e32 v37, v37, v86, vcc
	v_rsq_f32_e32 v37, v37
	s_nop 0
	v_mul_f32_e32 v86, 0x45800000, v37
	v_cndmask_b32_e32 v86, v37, v86, vcc
	v_pk_mul_f32 v[38:39], v[38:39], v[86:87] op_sel_hi:[1,0]
	v_pk_mul_f32 v[40:41], v[40:41], v[86:87] op_sel_hi:[1,0]
	v_pk_mul_f32 v[42:43], v[42:43], v[86:87] op_sel_hi:[1,0]
	v_pk_mul_f32 v[44:45], v[44:45], v[86:87] op_sel_hi:[1,0]
	v_pk_mul_f32 v[46:47], v[46:47], v[86:87] op_sel_hi:[1,0]
	v_pk_mul_f32 v[48:49], v[48:49], v[86:87] op_sel_hi:[1,0]
	v_pk_mul_f32 v[50:51], v[50:51], v[86:87] op_sel_hi:[1,0]
	v_pk_mul_f32 v[52:53], v[52:53], v[86:87] op_sel_hi:[1,0]
	v_pk_mul_f32 v[38:39], v[0:1], v[38:39]
	v_pk_mul_f32 v[40:41], v[2:3], v[40:41]
	v_pk_mul_f32 v[42:43], v[4:5], v[42:43]
	v_pk_mul_f32 v[44:45], v[6:7], v[44:45]
	v_pk_mul_f32 v[46:47], v[8:9], v[46:47]
	v_pk_mul_f32 v[48:49], v[10:11], v[48:49]
	v_pk_mul_f32 v[50:51], v[12:13], v[50:51]
	v_pk_mul_f32 v[52:53], v[14:15], v[52:53]
	s_waitcnt vmcnt(5)
	v_pk_fma_f32 v[38:39], v[62:63], v[38:39], v[78:79]
	v_pk_fma_f32 v[40:41], v[64:65], v[40:41], v[80:81]
	v_pk_fma_f32 v[42:43], v[66:67], v[42:43], v[54:55]
	v_pk_fma_f32 v[44:45], v[68:69], v[44:45], v[56:57]
	v_pk_fma_f32 v[46:47], v[70:71], v[46:47], v[58:59]
	v_pk_fma_f32 v[48:49], v[72:73], v[48:49], v[60:61]
	s_waitcnt vmcnt(4)
	v_pk_fma_f32 v[50:51], v[74:75], v[50:51], v[82:83]
	v_pk_fma_f32 v[52:53], v[76:77], v[52:53], v[84:85]
	v_cvt_pk_bf16_f32 v38, v38, v39
	v_cvt_pk_bf16_f32 v39, v40, v41
	v_cvt_pk_bf16_f32 v40, v42, v43
	v_cvt_pk_bf16_f32 v41, v44, v45
	v_cvt_pk_bf16_f32 v42, v46, v47
	v_cvt_pk_bf16_f32 v43, v48, v49
	v_cvt_pk_bf16_f32 v44, v50, v51
	v_cvt_pk_bf16_f32 v45, v52, v53
	global_store_dwordx2 v[20:21], v[38:39], off
	global_store_dwordx2 v[20:21], v[40:41], off offset:512
	global_store_dwordx2 v[20:21], v[42:43], off offset:1024
	global_store_dwordx2 v[20:21], v[44:45], off offset:1536
	v_lshl_add_u64 v[20:21], v[20:21], 0, s[10:11]
	s_andn2_b64 exec, exec, s[16:17]
	s_cbranch_execnz .LBB0_236

; __device__ __forceinline__ float bf_lo(unsigned u) { return __uint_as_float(u << 16); }
; __device__ __forceinline__ float bf_hi(unsigned u) { return __uint_as_float(u & 0xffff0000u); }
; __device__ __forceinline__ int vblk() { return (int)blockIdx.x * 2 + half_id(); }
; __device__ __forceinline__ int vgrid() { return (int)gridDim.x * 2; }
; __device__ void phase_modnorm(const Params& p, const float* __restrict__ src, const bf16_t* __restrict__ srcb, const float* __restrict__ g, int shift_idx, int scale_idx, bf16_t* __restrict__ dst) {
;     const int tid_ = TIDX; const int lane = tid_ & 63, wave = tid_ >> 6;
;     const float* mod = (const float*)(p.ws + OFF_MOD);
;     for (int tok = vblk() * 4 + wave; tok < NTOK; tok += vgrid() * 4) {
;         const int b = tok >> 11;
;         const float* xr = src + (size_t)tok * DM;
;         f32x4 v[4];
;         float ss = 0.f;
; #pragma unroll
;         for (int c = 0; c < 4; c++) {
;             if (srcb) {
;                 const u32x2 w = *(const u32x2*)(srcb + (size_t)tok * DM + c * 256 + lane * 4);
;                 v[c] = (f32x4){bf_lo(w.x), bf_hi(w.x), bf_lo(w.y), bf_hi(w.y)};
;             } else v[c] = *(const f32x4*)(xr + c * 256 + lane * 4);
.LBB0_852:
	s_or_b64 exec, exec, s[4:5]
	v_readfirstlane_b32 s0, v158
	s_lshr_b32 s0, s0, 6
	s_mov_b64 s[6:7], s[80:81]
	v_mov_b32_e32 v18, v158
	s_and_b32 s0, s0, 0x3fffffc
	s_waitcnt lgkmcnt(0)
	s_barrier
	s_add_i32 s0, s0, s28
	v_lshrrev_b32_e32 v0, 6, v18
	v_and_or_b32 v16, v0, 3, s0
	s_movk_i32 s0, 0x4000
	v_cmp_gt_i32_e32 vcc, s0, v16
	s_and_saveexec_b64 s[4:5], vcc
	s_cbranch_execz .LBB0_855
	s_load_dwordx2 s[0:1], s[6:7], 0x30
	v_lshlrev_b32_e32 v0, 2, v18
	v_and_b32_e32 v22, 0xfc, v0
	v_lshlrev_b32_e32 v17, 2, v22
	v_xor_b32_e32 v20, 32, v159
	s_waitcnt lgkmcnt(0)
	global_load_dwordx4 v[0:3], v17, s[0:1]
	global_load_dwordx4 v[4:7], v17, s[0:1] offset:1024
	global_load_dwordx4 v[8:11], v17, s[0:1] offset:2048
	global_load_dwordx4 v[12:15], v17, s[0:1] offset:3072
	v_and_b32_e32 v17, 64, v159
	v_add_u32_e32 v17, 64, v17
	v_cmp_lt_i32_e32 vcc, v20, v17
	s_load_dwordx2 s[0:1], s[6:7], 0xd8
	v_mov_b32_e32 v19, 0
	v_cndmask_b32_e32 v20, v159, v20, vcc
	v_lshlrev_b32_e32 v28, 2, v20
	v_xor_b32_e32 v20, 16, v159
	v_cmp_lt_i32_e32 vcc, v20, v17
	s_waitcnt lgkmcnt(0)
	s_add_u32 s8, s0, 0x4000
	s_addc_u32 s9, s1, 0
	v_cndmask_b32_e32 v20, v159, v20, vcc
	v_lshlrev_b32_e32 v29, 2, v20
	v_xor_b32_e32 v20, 8, v159
	v_cmp_lt_i32_e32 vcc, v20, v17
	s_lshl_b32 s10, s72, 3
	v_or_b32_e32 v24, 0x100, v22
	v_cndmask_b32_e32 v20, v159, v20, vcc
	v_lshlrev_b32_e32 v30, 2, v20
	v_xor_b32_e32 v20, 4, v159
	v_cmp_lt_i32_e32 vcc, v20, v17
	v_or_b32_e32 v26, 0x200, v22
	v_or_b32_e32 v34, 0x300, v22
	v_cndmask_b32_e32 v20, v159, v20, vcc
	v_lshlrev_b32_e32 v31, 2, v20
	v_xor_b32_e32 v20, 2, v159
	v_cmp_lt_i32_e32 vcc, v20, v17
	s_ashr_i32 s11, s10, 31
	s_mov_b64 s[6:7], 0x4000
	v_cndmask_b32_e32 v20, v159, v20, vcc
	v_lshlrev_b32_e32 v32, 2, v20
	v_xor_b32_e32 v20, 1, v159
	v_cmp_lt_i32_e32 vcc, v20, v17
	s_lshl_b64 s[12:13], s[10:11], 11
	s_mov_b64 s[14:15], 0
	v_cndmask_b32_e32 v17, v159, v20, vcc
	v_lshlrev_b32_e32 v33, 2, v17
	v_ashrrev_i32_e32 v17, 31, v16
	v_lshlrev_b64 v[20:21], 11, v[16:17]
	v_and_b32_e32 v17, 63, v18
	v_lshl_or_b32 v20, v17, 3, v20
	v_lshl_add_u64 v[20:21], s[0:1], 0, v[20:21]
	s_mov_b64 s[0:1], 0xbd00000
	v_lshl_add_u64 v[20:21], v[20:21], 0, s[0:1]
	s_mov_b64 s[16:17], 0x3000
	v_lshlrev_b32_e32 v18, 2, v22
	v_lshlrev_b32_e32 v22, 2, v24
	v_mov_b32_e32 v23, v19
	v_lshlrev_b32_e32 v24, 2, v26
	v_mov_b32_e32 v25, v19
	v_lshlrev_b32_e32 v26, 2, v34
	v_mov_b32_e32 v27, v19
	v_mov_b32_e32 v17, 0x358637bd
	s_mov_b32 s0, 0x800000
	s_mov_b32 s1, 0xf5f00000
	s_mov_b32 s2, 0xf5f01000
	s_movk_i32 s3, 0x3fff
	global_load_dwordx2 v[120:121], v[20:21], off
	global_load_dwordx2 v[122:123], v[20:21], off offset:512
	global_load_dwordx2 v[124:125], v[20:21], off offset:1024
	global_load_dwordx2 v[126:127], v[20:21], off offset:1536
	s_waitcnt vmcnt(0)
	s_branch .Lmn2_body

; __device__ __forceinline__ float bf_lo(unsigned u) { return __uint_as_float(u << 16); }
; __device__ __forceinline__ float bf_hi(unsigned u) { return __uint_as_float(u & 0xffff0000u); }
; __device__ __forceinline__ int vblk() { return (int)blockIdx.x * 2 + half_id(); }
; __device__ __forceinline__ int vgrid() { return (int)gridDim.x * 2; }
; __device__ void phase_modnorm(const Params& p, const float* __restrict__ src, const bf16_t* __restrict__ srcb, const float* __restrict__ g, int shift_idx, int scale_idx, bf16_t* __restrict__ dst) {
;     ...
;     for (int tok = vblk() * 4 + wave; tok < NTOK; tok += vgrid() * 4) {
;         const int b = tok >> 11;
;         const float* xr = src + (size_t)tok * DM;
;         f32x4 v[4];
;         float ss = 0.f;
; #pragma unroll
;         for (int c = 0; c < 4; c++) {
;             if (srcb) {
;                 const u32x2 w = *(const u32x2*)(srcb + (size_t)tok * DM + c * 256 + lane * 4);
;                 v[c] = (f32x4){bf_lo(w.x), bf_hi(w.x), bf_lo(w.y), bf_hi(w.y)};
;             } else v[c] = *(const f32x4*)(xr + c * 256 + lane * 4);
;             ss += v[c][0] * v[c][0] + v[c][1] * v[c][1] + v[c][2] * v[c][2] + v[c][3] * v[c][3];
;         }
;         ss = wave_sum(ss);
;         const float rstd = rsqrtf(ss * (1.f / 1024.f) + 1e-6f);
; #pragma unroll
;         for (int c = 0; c < 4; c++) {
;             const int d = c * 256 + lane * 4;
;             const f32x4 gg = *(const f32x4*)(g + d);
;             const f32x4 sc = *(const f32x4*)(mod + b * 6144 + scale_idx * 1024 + d);
;             const f32x4 sh = *(const f32x4*)(mod + b * 6144 + shift_idx * 1024 + d);
;             float o[4];
; #pragma unroll
;             for (int j = 0; j < 4; j++) o[j] = (v[c][j] * rstd) * gg[j] * (1.f + sc[j]) + sh[j];
;             *(u32x2*)(dst + (size_t)tok * DM + d) = (u32x2){pack2(o[0], o[1]), pack2(o[2], o[3])};
;         }
.Lmn2_body:
	v_mov_b32_e32 v66, v120
	v_mov_b32_e32 v67, v121
	v_mov_b32_e32 v68, v122
	v_mov_b32_e32 v69, v123
	v_mov_b32_e32 v70, v124
	v_mov_b32_e32 v71, v125
	v_mov_b32_e32 v72, v126
	v_mov_b32_e32 v73, v127
	v_ashrrev_i32_e32 v34, 11, v16
	v_mul_i32_i24_e32 v34, 0x1800, v34
	v_ashrrev_i32_e32 v35, 31, v34
	v_lshl_add_u64 v[34:35], v[34:35], 2, s[8:9]
	v_lshl_add_u64 v[36:37], v[34:35], 0, s[6:7]
	v_lshl_add_u64 v[34:35], v[34:35], 0, s[16:17]
	v_lshl_add_u64 v[78:79], v[36:37], 0, v[18:19]
	v_lshl_add_u64 v[80:81], v[34:35], 0, v[18:19]
	v_lshl_add_u64 v[82:83], v[36:37], 0, v[22:23]
	v_lshl_add_u64 v[84:85], v[34:35], 0, v[22:23]
	v_lshl_add_u64 v[86:87], v[36:37], 0, v[24:25]
	v_lshl_add_u64 v[88:89], v[34:35], 0, v[24:25]
	v_lshl_add_u64 v[90:91], v[36:37], 0, v[26:27]
	v_lshl_add_u64 v[92:93], v[34:35], 0, v[26:27]
	global_load_dwordx4 v[34:37], v[78:79], off
	global_load_dwordx4 v[38:41], v[82:83], off
	global_load_dwordx4 v[42:45], v[86:87], off
	global_load_dwordx4 v[46:49], v[90:91], off
	global_load_dwordx4 v[50:53], v[80:81], off
	global_load_dwordx4 v[54:57], v[84:85], off
	global_load_dwordx4 v[58:61], v[88:89], off
	global_load_dwordx4 v[62:65], v[92:93], off
	v_add_co_u32_e32 v74, vcc, s1, v20
	v_add_u32_e32 v16, s10, v16
	s_nop 0
	v_addc_co_u32_e32 v75, vcc, -1, v21, vcc
	v_add_co_u32_e32 v76, vcc, s2, v20
	v_and_b32_e32 v81, 0xffff0000, v66
	v_and_b32_e32 v83, 0xffff0000, v68
	v_lshlrev_b32_e32 v80, 16, v66
	v_lshlrev_b32_e32 v82, 16, v68
	v_and_b32_e32 v85, 0xffff0000, v70
	v_and_b32_e32 v87, 0xffff0000, v72
	v_mov_b32_e32 v92, v81
	v_mov_b32_e32 v93, v83
	v_lshlrev_b32_e32 v78, 16, v67
	v_lshlrev_b32_e32 v66, 16, v69
	v_lshlrev_b32_e32 v84, 16, v70
	v_lshlrev_b32_e32 v86, 16, v72
	v_mov_b32_e32 v90, v80
	v_mov_b32_e32 v91, v82
	v_mov_b32_e32 v100, v85
	v_mov_b32_e32 v101, v87
	v_pk_mul_f32 v[92:93], v[92:93], v[92:93]
	v_and_b32_e32 v79, 0xffff0000, v67
	v_and_b32_e32 v67, 0xffff0000, v69
	v_lshlrev_b32_e32 v68, 16, v71
	v_and_b32_e32 v69, 0xffff0000, v71
	v_lshlrev_b32_e32 v70, 16, v73
	v_and_b32_e32 v71, 0xffff0000, v73
	v_mov_b32_e32 v72, v78
	v_mov_b32_e32 v73, v66
	v_mov_b32_e32 v98, v84
	v_mov_b32_e32 v99, v86
	v_pk_mul_f32 v[100:101], v[100:101], v[100:101]
	v_pk_fma_f32 v[90:91], v[90:91], v[90:91], v[92:93]
	v_mov_b32_e32 v88, v79
	v_mov_b32_e32 v89, v67
	v_mov_b32_e32 v94, v68
	v_mov_b32_e32 v95, v70
	v_pk_fma_f32 v[92:93], v[98:99], v[98:99], v[100:101]
	v_pk_fma_f32 v[72:73], v[72:73], v[72:73], v[90:91]
	v_mov_b32_e32 v96, v69
	v_mov_b32_e32 v97, v71
	v_pk_fma_f32 v[90:91], v[94:95], v[94:95], v[92:93]
	v_pk_fma_f32 v[72:73], v[88:89], v[88:89], v[72:73]
	v_pk_fma_f32 v[88:89], v[96:97], v[96:97], v[90:91]
	v_add_f32_e32 v72, v72, v73
	v_add_f32_e32 v72, v72, v88
	v_add_f32_e32 v72, v72, v89
	s_nop 1
	v_add_f32_dpp v72, v72, v72 row_ror:8 row_mask:0xf bank_mask:0xf
	s_nop 1
	v_add_f32_dpp v72, v72, v72 row_ror:4 row_mask:0xf bank_mask:0xf
	s_nop 1
	v_add_f32_dpp v72, v72, v72 row_ror:2 row_mask:0xf bank_mask:0xf
	s_nop 1
	v_add_f32_dpp v72, v72, v72 row_ror:1 row_mask:0xf bank_mask:0xf
	v_mov_b32_e32 v73, v72
	s_nop 1
	v_permlane16_swap_b32_e32 v72, v73
	v_add_f32_e32 v72, v72, v73
	v_mov_b32_e32 v73, v72
	s_nop 1
	v_permlane32_swap_b32_e32 v72, v73
	v_add_f32_e32 v72, v72, v73
	v_addc_co_u32_e32 v77, vcc, -1, v21, vcc
	v_cmp_lt_i32_e32 vcc, s3, v16
	s_or_b64 s[14:15], vcc, s[14:15]
	s_waitcnt vmcnt(7)
	v_pk_add_f32 v[34:35], v[34:35], 1.0 op_sel_hi:[1,0]
	v_pk_add_f32 v[36:37], v[36:37], 1.0 op_sel_hi:[1,0]
	s_waitcnt vmcnt(6)
	v_pk_add_f32 v[38:39], v[38:39], 1.0 op_sel_hi:[1,0]
	v_pk_add_f32 v[40:41], v[40:41], 1.0 op_sel_hi:[1,0]
	s_waitcnt vmcnt(5)
	v_pk_add_f32 v[42:43], v[42:43], 1.0 op_sel_hi:[1,0]
	v_pk_add_f32 v[44:45], v[44:45], 1.0 op_sel_hi:[1,0]
	s_waitcnt vmcnt(4)
	v_pk_add_f32 v[46:47], v[46:47], 1.0 op_sel_hi:[1,0]
	v_pk_add_f32 v[48:49], v[48:49], 1.0 op_sel_hi:[1,0]
	v_mov_b32_e32 v128, v20
	v_mov_b32_e32 v129, v21
	v_lshl_add_u64 v[20:21], v[20:21], 0, s[12:13]
	v_cndmask_b32_e32 v128, v20, v128, vcc
	v_cndmask_b32_e32 v129, v21, v129, vcc
	global_load_dwordx2 v[120:121], v[128:129], off
	global_load_dwordx2 v[122:123], v[128:129], off offset:512
	global_load_dwordx2 v[124:125], v[128:129], off offset:1024
	global_load_dwordx2 v[126:127], v[128:129], off offset:1536
	v_fmamk_f32 v72, v72, 0x3a800000, v17
	v_mul_f32_e32 v73, 0x4b800000, v72
	v_cmp_gt_f32_e32 vcc, s0, v72
	s_nop 1
	v_cndmask_b32_e32 v72, v72, v73, vcc
	v_rsq_f32_e32 v72, v72
	s_nop 0
	v_mul_f32_e32 v73, 0x45800000, v72
	v_cndmask_b32_e32 v72, v72, v73, vcc
	v_pk_mul_f32 v[80:81], v[72:73], v[80:81] op_sel_hi:[0,1]
	v_pk_mul_f32 v[78:79], v[72:73], v[78:79] op_sel_hi:[0,1]
	v_pk_mul_f32 v[82:83], v[72:73], v[82:83] op_sel_hi:[0,1]
	v_pk_mul_f32 v[66:67], v[72:73], v[66:67] op_sel_hi:[0,1]
	v_pk_mul_f32 v[84:85], v[72:73], v[84:85] op_sel_hi:[0,1]
	v_pk_mul_f32 v[68:69], v[72:73], v[68:69] op_sel_hi:[0,1]
	v_pk_mul_f32 v[86:87], v[72:73], v[86:87] op_sel_hi:[0,1]
	v_pk_mul_f32 v[70:71], v[72:73], v[70:71] op_sel_hi:[0,1]
	v_pk_mul_f32 v[72:73], v[0:1], v[80:81]
	v_pk_mul_f32 v[78:79], v[2:3], v[78:79]
	v_pk_mul_f32 v[80:81], v[4:5], v[82:83]
	v_pk_mul_f32 v[66:67], v[6:7], v[66:67]
	v_pk_mul_f32 v[82:83], v[8:9], v[84:85]
	v_pk_mul_f32 v[68:69], v[10:11], v[68:69]
	v_pk_mul_f32 v[84:85], v[12:13], v[86:87]
	v_pk_mul_f32 v[70:71], v[14:15], v[70:71]
	s_waitcnt vmcnt(7)
	v_pk_fma_f32 v[34:35], v[34:35], v[72:73], v[50:51]
	v_pk_fma_f32 v[36:37], v[36:37], v[78:79], v[52:53]
	s_waitcnt vmcnt(6)
	v_pk_fma_f32 v[38:39], v[38:39], v[80:81], v[54:55]
	v_pk_fma_f32 v[40:41], v[40:41], v[66:67], v[56:57]
	s_waitcnt vmcnt(5)
	v_pk_fma_f32 v[42:43], v[42:43], v[82:83], v[58:59]
	v_pk_fma_f32 v[44:45], v[44:45], v[68:69], v[60:61]
	s_waitcnt vmcnt(4)
	v_pk_fma_f32 v[46:47], v[46:47], v[84:85], v[62:63]
	v_pk_fma_f32 v[48:49], v[48:49], v[70:71], v[64:65]
	v_cvt_pk_bf16_f32 v34, v34, v35
	v_cvt_pk_bf16_f32 v35, v36, v37
	v_cvt_pk_bf16_f32 v36, v38, v39
	v_cvt_pk_bf16_f32 v37, v40, v41
	v_cvt_pk_bf16_f32 v38, v42, v43
	v_cvt_pk_bf16_f32 v39, v44, v45
	v_cvt_pk_bf16_f32 v40, v46, v47
	v_cvt_pk_bf16_f32 v41, v48, v49
	global_store_dwordx2 v[74:75], v[34:35], off
	global_store_dwordx2 v[76:77], v[36:37], off offset:-3584
	global_store_dwordx2 v[76:77], v[38:39], off offset:-3072
	global_store_dwordx2 v[76:77], v[40:41], off offset:-2560
	s_andn2_b64 exec, exec, s[14:15]
	s_cbranch_execnz .LBB0_854
